# in-proj rotary epilogue: cos/sin table loads hoisted out of the 16-step load-wait-store ladder
# baseline (speedup 1.0000x reference)
; __device__ __forceinline__ unsigned pk2(float lo, float hi) { f32x2 v = {lo, hi}; bf16x2_t b = __builtin_convertvector(v, bf16x2_t); return __builtin_bit_cast(unsigned, b); }
; __device__ __forceinline__ void swap16(unsigned& a, unsigned& b) { auto r = __builtin_amdgcn_permlane16_swap(a, b, false, false); a = r[0]; b = r[1]; }
;     __device__ __forceinline__ void operator()(const f32x4 (&acc)[2][2][4][2], const Unit& u, int wr, int wc, int fr, int fq) const {
;     ...
;         if (u.pn < 8) {
; #pragma unroll
;             for (int ai = 0; ai < 2; ++ai)
; #pragma unroll
;                 for (int m = 0; m < 4; ++m) {
;                     const int row = row0 + ai * HALF + m * 16, pos = row & (SEQ - 1);
; #pragma unroll
;                     for (int bj = 0; bj < 2; ++bj) {
;                         const int g = 4 * bj + wc, hl = g >> 1, d0 = (g & 1) * 16 + 4 * fq;
;                         const f32x4 c = *(const f32x4*)(cosT + pos * 32 + d0), s = *(const f32x4*)(sinT + pos * 32 + d0);
;                         const f32x4 x1 = acc[ai][bj][m][0], x2 = acc[ai][bj][m][1];
;                         const float qs = (u.pn < 4) ? 0.125f * 1.4426950408889634f : 1.0f;
;                         const f32x4 o1 = (x1 * c - x2 * s) * qs, o2 = (x2 * c + x1 * s) * qs;
;                         bf16_t* p = P + (size_t)row * INC + u.pn * BM + hl * 64 + d0;
;                         unsigned a0 = pk2(o1[0], o1[1]), a1 = pk2(o1[2], o1[3]), b0 = pk2(o2[0], o2[1]), b1 = pk2(o2[2], o2[3]);
;                         swap16(a0, b0); swap16(a1, b1);
;                         *(u32x4*)(p + ((fq & 1) ? 28 : 0)) = (u32x4){a0, a1, b0, b1};
;                         asm volatile("" ::: "memory");
;                     }
;                 }
.LBB0_163:
	v_mov_b32_e32 v251, 0
	v_lshlrev_b32_e32 v250, 7, v143
	v_and_b32_e32 v250, 0xfe780, v250
	v_lshl_add_u64 v[252:253], v[134:135], 0, v[250:251]
	global_load_dwordx4 v[192:195], v[252:253], off
	v_lshl_add_u64 v[252:253], v[136:137], 0, v[250:251]
	global_load_dwordx4 v[196:199], v[252:253], off
	v_lshlrev_b32_e32 v250, 7, v179
	v_and_b32_e32 v250, 0xfef80, v250
	v_lshl_add_u64 v[252:253], v[134:135], 0, v[250:251]
	global_load_dwordx4 v[200:203], v[252:253], off
	v_lshl_add_u64 v[252:253], v[136:137], 0, v[250:251]
	global_load_dwordx4 v[204:207], v[252:253], off
	v_lshlrev_b32_e32 v250, 7, v178
	v_and_b32_e32 v250, 0xff780, v250
	v_lshl_add_u64 v[252:253], v[134:135], 0, v[250:251]
	global_load_dwordx4 v[208:211], v[252:253], off
	v_lshl_add_u64 v[252:253], v[136:137], 0, v[250:251]
	global_load_dwordx4 v[222:225], v[252:253], off
	v_lshlrev_b32_e32 v250, 7, v177
	v_and_b32_e32 v250, 0xfff80, v250
	v_lshl_add_u64 v[252:253], v[134:135], 0, v[250:251]
	global_load_dwordx4 v[226:229], v[252:253], off
	v_lshl_add_u64 v[252:253], v[136:137], 0, v[250:251]
	global_load_dwordx4 v[230:233], v[252:253], off
	v_lshlrev_b32_e32 v250, 7, v176
	v_and_b32_e32 v250, 0xfe780, v250
	v_lshl_add_u64 v[252:253], v[134:135], 0, v[250:251]
	global_load_dwordx4 v[234:237], v[252:253], off
	v_lshl_add_u64 v[252:253], v[136:137], 0, v[250:251]
	global_load_dwordx4 v[238:241], v[252:253], off
	v_lshlrev_b32_e32 v250, 7, v175
	v_and_b32_e32 v250, 0xfef80, v250
	v_lshl_add_u64 v[252:253], v[134:135], 0, v[250:251]
	global_load_dwordx4 v[242:245], v[252:253], off
	v_lshl_add_u64 v[252:253], v[136:137], 0, v[250:251]
	global_load_dwordx4 v[246:249], v[252:253], off
	s_cmp_lt_i32 s33, 4
	s_cselect_b64 vcc, -1, 0
	v_mov_b32_e32 v0, 0x3e38aa3b
	v_cndmask_b32_e32 v164, 1.0, v0, vcc
	v_lshlrev_b32_e32 v0, 7, v143
	v_and_b32_e32 v0, 0xfe780, v0
	v_lshl_add_u64 v[166:167], v[134:135], 0, v[0:1]
	v_lshl_add_u64 v[168:169], v[136:137], 0, v[0:1]
	s_lshl_b32 s66, s33, 8
	s_ashr_i32 s67, s66, 31
	s_movk_i32 s33, 0x3800
	s_lshl_b64 s[66:67], s[66:67], 1
	v_mov_b32_e32 v145, v1
	v_lshlrev_b32_e32 v0, 7, v179
	v_and_b32_e32 v0, 0xfef80, v0
	s_waitcnt vmcnt(0)
	v_pk_mul_f32 v[190:191], v[122:123], v[196:197]
	v_pk_mul_f32 v[188:189], v[124:125], v[198:199]
	v_pk_fma_f32 v[190:191], v[126:127], v[192:193], v[190:191] neg_lo:[0,0,1] neg_hi:[0,0,1]
	v_pk_mul_f32 v[126:127], v[126:127], v[196:197]
	v_pk_fma_f32 v[188:189], v[128:129], v[194:195], v[188:189] neg_lo:[0,0,1] neg_hi:[0,0,1]
	v_pk_mul_f32 v[128:129], v[128:129], v[198:199]
	v_pk_fma_f32 v[122:123], v[122:123], v[192:193], v[126:127]
	v_pk_fma_f32 v[124:125], v[124:125], v[194:195], v[128:129]
	v_pk_mul_f32 v[126:127], v[164:165], v[122:123] op_sel_hi:[0,1]
	v_mov_b64_e32 v[122:123], s[40:41]
	v_pk_mul_f32 v[128:129], v[164:165], v[124:125] op_sel_hi:[0,1]
	v_mad_i64_i32 v[124:125], s[68:69], v143, s33, v[122:123]
	v_lshl_add_u64 v[124:125], v[124:125], 0, s[66:67]
	v_pk_mul_f32 v[188:189], v[164:165], v[188:189] op_sel_hi:[0,1]
	v_pk_mul_f32 v[190:191], v[164:165], v[190:191] op_sel_hi:[0,1]
	v_lshl_add_u64 v[124:125], v[124:125], 0, s[36:37]
	v_mov_b32_e32 v143, v1
	v_lshl_add_u64 v[180:181], v[124:125], 0, v[142:143]
	v_cvt_pk_bf16_f32 v124, v190, v191
	v_cvt_pk_bf16_f32 v125, v188, v189
	v_cvt_pk_bf16_f32 v126, v126, v127
	v_cvt_pk_bf16_f32 v127, v128, v129
	s_nop 0
	v_permlane16_swap_b32_e32 v124, v126
	v_permlane16_swap_b32_e32 v125, v127
	v_lshl_add_u64 v[128:129], v[180:181], 0, v[144:145]
	global_store_dwordx4 v[128:129], v[124:127], off
	s_nop 0
	v_pk_mul_f32 v[180:181], v[116:117], v[198:199]
	v_pk_mul_f32 v[182:183], v[114:115], v[196:197]
	v_pk_fma_f32 v[180:181], v[120:121], v[194:195], v[180:181] neg_lo:[0,0,1] neg_hi:[0,0,1]
	v_pk_fma_f32 v[182:183], v[118:119], v[192:193], v[182:183] neg_lo:[0,0,1] neg_hi:[0,0,1]
	v_pk_mul_f32 v[120:121], v[120:121], v[198:199]
	v_pk_mul_f32 v[118:119], v[118:119], v[196:197]
	v_pk_fma_f32 v[116:117], v[116:117], v[194:195], v[120:121]
	v_pk_fma_f32 v[114:115], v[114:115], v[192:193], v[118:119]
	v_pk_mul_f32 v[180:181], v[164:165], v[180:181] op_sel_hi:[0,1]
	v_pk_mul_f32 v[182:183], v[164:165], v[182:183] op_sel_hi:[0,1]
	v_pk_mul_f32 v[118:119], v[164:165], v[116:117] op_sel_hi:[0,1]
	v_pk_mul_f32 v[116:117], v[164:165], v[114:115] op_sel_hi:[0,1]
	v_cvt_pk_bf16_f32 v114, v182, v183
	v_cvt_pk_bf16_f32 v115, v180, v181
	v_cvt_pk_bf16_f32 v116, v116, v117
	v_cvt_pk_bf16_f32 v117, v118, v119
	s_nop 0
	v_permlane16_swap_b32_e32 v114, v116
	v_permlane16_swap_b32_e32 v115, v117
	global_store_dwordx4 v[128:129], v[114:117], off offset:256
	s_nop 1
	v_lshl_add_u64 v[114:115], v[134:135], 0, v[0:1]
	v_lshl_add_u64 v[116:117], v[136:137], 0, v[0:1]
	v_lshlrev_b32_e32 v0, 7, v178
	v_and_b32_e32 v0, 0xff780, v0
	v_pk_mul_f32 v[128:129], v[108:109], v[206:207]
	v_pk_mul_f32 v[166:167], v[106:107], v[204:205]
	v_pk_fma_f32 v[128:129], v[112:113], v[202:203], v[128:129] neg_lo:[0,0,1] neg_hi:[0,0,1]
	v_pk_fma_f32 v[166:167], v[110:111], v[200:201], v[166:167] neg_lo:[0,0,1] neg_hi:[0,0,1]
	v_pk_mul_f32 v[112:113], v[112:113], v[206:207]
	v_pk_mul_f32 v[110:111], v[110:111], v[204:205]
	v_pk_fma_f32 v[108:109], v[108:109], v[202:203], v[112:113]
	v_pk_fma_f32 v[106:107], v[106:107], v[200:201], v[110:111]
	v_pk_mul_f32 v[110:111], v[164:165], v[108:109] op_sel_hi:[0,1]
	v_pk_mul_f32 v[108:109], v[164:165], v[106:107] op_sel_hi:[0,1]
	v_mad_i64_i32 v[106:107], s[68:69], v179, s33, v[122:123]
	v_lshl_add_u64 v[106:107], v[106:107], 0, s[66:67]
	v_pk_mul_f32 v[128:129], v[164:165], v[128:129] op_sel_hi:[0,1]
	v_pk_mul_f32 v[166:167], v[164:165], v[166:167] op_sel_hi:[0,1]
; __device__ __forceinline__ unsigned pk2(float lo, float hi) { f32x2 v = {lo, hi}; bf16x2_t b = __builtin_convertvector(v, bf16x2_t); return __builtin_bit_cast(unsigned, b); }
; __device__ __forceinline__ void swap16(unsigned& a, unsigned& b) { auto r = __builtin_amdgcn_permlane16_swap(a, b, false, false); a = r[0]; b = r[1]; }
;     __device__ __forceinline__ void operator()(const f32x4 (&acc)[2][2][4][2], const Unit& u, int wr, int wc, int fr, int fq) const {
;     ...
;         if (u.pn < 8) {
; #pragma unroll
;             for (int ai = 0; ai < 2; ++ai)
; #pragma unroll
;                 for (int m = 0; m < 4; ++m) {
;                     const int row = row0 + ai * HALF + m * 16, pos = row & (SEQ - 1);
; #pragma unroll
;                     for (int bj = 0; bj < 2; ++bj) {
;                         const int g = 4 * bj + wc, hl = g >> 1, d0 = (g & 1) * 16 + 4 * fq;
;                         const f32x4 c = *(const f32x4*)(cosT + pos * 32 + d0), s = *(const f32x4*)(sinT + pos * 32 + d0);
;                         const f32x4 x1 = acc[ai][bj][m][0], x2 = acc[ai][bj][m][1];
;                         const float qs = (u.pn < 4) ? 0.125f * 1.4426950408889634f : 1.0f;
;                         const f32x4 o1 = (x1 * c - x2 * s) * qs, o2 = (x2 * c + x1 * s) * qs;
;                         bf16_t* p = P + (size_t)row * INC + u.pn * BM + hl * 64 + d0;
;                         unsigned a0 = pk2(o1[0], o1[1]), a1 = pk2(o1[2], o1[3]), b0 = pk2(o2[0], o2[1]), b1 = pk2(o2[2], o2[3]);
;                         swap16(a0, b0); swap16(a1, b1);
;                         *(u32x4*)(p + ((fq & 1) ? 28 : 0)) = (u32x4){a0, a1, b0, b1};
;                         asm volatile("" ::: "memory");
;                     }
;                 }
	v_lshl_add_u64 v[106:107], v[106:107], 0, s[36:37]
	v_lshl_add_u64 v[112:113], v[106:107], 0, v[142:143]
	v_cvt_pk_bf16_f32 v106, v166, v167
	v_cvt_pk_bf16_f32 v107, v128, v129
	v_cvt_pk_bf16_f32 v108, v108, v109
	v_cvt_pk_bf16_f32 v109, v110, v111
	s_nop 0
	v_permlane16_swap_b32_e32 v106, v108
	v_permlane16_swap_b32_e32 v107, v109
	v_lshl_add_u64 v[118:119], v[112:113], 0, v[144:145]
	global_store_dwordx4 v[118:119], v[106:109], off
	v_pk_mul_f32 v[114:115], v[100:101], v[206:207]
	v_pk_mul_f32 v[116:117], v[98:99], v[204:205]
	v_pk_fma_f32 v[114:115], v[104:105], v[202:203], v[114:115] neg_lo:[0,0,1] neg_hi:[0,0,1]
	v_pk_fma_f32 v[116:117], v[102:103], v[200:201], v[116:117] neg_lo:[0,0,1] neg_hi:[0,0,1]
	v_pk_mul_f32 v[104:105], v[104:105], v[206:207]
	v_pk_mul_f32 v[102:103], v[102:103], v[204:205]
	v_pk_fma_f32 v[100:101], v[100:101], v[202:203], v[104:105]
	v_pk_fma_f32 v[98:99], v[98:99], v[200:201], v[102:103]
	v_pk_mul_f32 v[114:115], v[164:165], v[114:115] op_sel_hi:[0,1]
	v_pk_mul_f32 v[116:117], v[164:165], v[116:117] op_sel_hi:[0,1]
	v_pk_mul_f32 v[102:103], v[164:165], v[100:101] op_sel_hi:[0,1]
	v_pk_mul_f32 v[100:101], v[164:165], v[98:99] op_sel_hi:[0,1]
	v_cvt_pk_bf16_f32 v98, v116, v117
	v_cvt_pk_bf16_f32 v99, v114, v115
	v_cvt_pk_bf16_f32 v100, v100, v101
	v_cvt_pk_bf16_f32 v101, v102, v103
	s_nop 0
	v_permlane16_swap_b32_e32 v98, v100
	v_permlane16_swap_b32_e32 v99, v101
	global_store_dwordx4 v[118:119], v[98:101], off offset:256
	v_lshlrev_b32_e32 v250, 7, v174
	v_and_b32_e32 v250, 0xff780, v250
	v_lshl_add_u64 v[252:253], v[134:135], 0, v[250:251]
	global_load_dwordx4 v[192:195], v[252:253], off
	v_lshl_add_u64 v[252:253], v[136:137], 0, v[250:251]
	global_load_dwordx4 v[196:199], v[252:253], off
	v_lshlrev_b32_e32 v250, 7, v173
	v_and_b32_e32 v250, 0xfff80, v250
	v_lshl_add_u64 v[252:253], v[134:135], 0, v[250:251]
	global_load_dwordx4 v[200:203], v[252:253], off
	v_lshl_add_u64 v[252:253], v[136:137], 0, v[250:251]
	global_load_dwordx4 v[204:207], v[252:253], off
	s_nop 1
	v_lshl_add_u64 v[98:99], v[134:135], 0, v[0:1]
	v_lshl_add_u64 v[100:101], v[136:137], 0, v[0:1]
	v_lshlrev_b32_e32 v0, 7, v177
	v_and_b32_e32 v0, 0xfff80, v0
	v_pk_mul_f32 v[110:111], v[92:93], v[224:225]
	v_pk_mul_f32 v[112:113], v[90:91], v[222:223]
	v_pk_fma_f32 v[110:111], v[96:97], v[210:211], v[110:111] neg_lo:[0,0,1] neg_hi:[0,0,1]
	v_pk_fma_f32 v[112:113], v[94:95], v[208:209], v[112:113] neg_lo:[0,0,1] neg_hi:[0,0,1]
	v_pk_mul_f32 v[96:97], v[96:97], v[224:225]
	v_pk_mul_f32 v[94:95], v[94:95], v[222:223]
	v_pk_fma_f32 v[92:93], v[92:93], v[210:211], v[96:97]
	v_pk_fma_f32 v[90:91], v[90:91], v[208:209], v[94:95]
	v_pk_mul_f32 v[94:95], v[164:165], v[92:93] op_sel_hi:[0,1]
	v_pk_mul_f32 v[92:93], v[164:165], v[90:91] op_sel_hi:[0,1]
	v_mad_i64_i32 v[90:91], s[68:69], v178, s33, v[122:123]
	v_lshl_add_u64 v[90:91], v[90:91], 0, s[66:67]
	v_pk_mul_f32 v[110:111], v[164:165], v[110:111] op_sel_hi:[0,1]
	v_pk_mul_f32 v[112:113], v[164:165], v[112:113] op_sel_hi:[0,1]
	v_lshl_add_u64 v[90:91], v[90:91], 0, s[36:37]
	v_lshl_add_u64 v[96:97], v[90:91], 0, v[142:143]
	v_cvt_pk_bf16_f32 v90, v112, v113
	v_cvt_pk_bf16_f32 v91, v110, v111
	v_cvt_pk_bf16_f32 v92, v92, v93
	v_cvt_pk_bf16_f32 v93, v94, v95
	s_nop 0
	v_permlane16_swap_b32_e32 v90, v92
	v_permlane16_swap_b32_e32 v91, v93
	v_lshl_add_u64 v[102:103], v[96:97], 0, v[144:145]
	global_store_dwordx4 v[102:103], v[90:93], off
	v_pk_mul_f32 v[98:99], v[84:85], v[224:225]
	v_pk_mul_f32 v[100:101], v[82:83], v[222:223]
	v_pk_fma_f32 v[98:99], v[88:89], v[210:211], v[98:99] neg_lo:[0,0,1] neg_hi:[0,0,1]
	v_pk_fma_f32 v[100:101], v[86:87], v[208:209], v[100:101] neg_lo:[0,0,1] neg_hi:[0,0,1]
	v_pk_mul_f32 v[88:89], v[88:89], v[224:225]
	v_pk_mul_f32 v[86:87], v[86:87], v[222:223]
	v_pk_fma_f32 v[84:85], v[84:85], v[210:211], v[88:89]
	v_pk_fma_f32 v[82:83], v[82:83], v[208:209], v[86:87]
	v_pk_mul_f32 v[98:99], v[164:165], v[98:99] op_sel_hi:[0,1]
	v_pk_mul_f32 v[100:101], v[164:165], v[100:101] op_sel_hi:[0,1]
	v_pk_mul_f32 v[86:87], v[164:165], v[84:85] op_sel_hi:[0,1]
	v_pk_mul_f32 v[84:85], v[164:165], v[82:83] op_sel_hi:[0,1]
	v_cvt_pk_bf16_f32 v82, v100, v101
	v_cvt_pk_bf16_f32 v83, v98, v99
	v_cvt_pk_bf16_f32 v84, v84, v85
	v_cvt_pk_bf16_f32 v85, v86, v87
	s_nop 0
	v_permlane16_swap_b32_e32 v82, v84
	v_permlane16_swap_b32_e32 v83, v85
	global_store_dwordx4 v[102:103], v[82:85], off offset:256
	s_nop 1
	v_lshl_add_u64 v[82:83], v[134:135], 0, v[0:1]
	v_lshl_add_u64 v[84:85], v[136:137], 0, v[0:1]
	v_lshlrev_b32_e32 v0, 7, v176
	v_and_b32_e32 v0, 0xfe780, v0
	v_pk_mul_f32 v[94:95], v[76:77], v[232:233]
	v_pk_mul_f32 v[96:97], v[74:75], v[230:231]
	v_pk_fma_f32 v[94:95], v[80:81], v[228:229], v[94:95] neg_lo:[0,0,1] neg_hi:[0,0,1]
	v_pk_fma_f32 v[96:97], v[78:79], v[226:227], v[96:97] neg_lo:[0,0,1] neg_hi:[0,0,1]
	v_pk_mul_f32 v[80:81], v[80:81], v[232:233]
	v_pk_mul_f32 v[78:79], v[78:79], v[230:231]
	v_pk_fma_f32 v[76:77], v[76:77], v[228:229], v[80:81]
	v_pk_fma_f32 v[74:75], v[74:75], v[226:227], v[78:79]
	v_pk_mul_f32 v[78:79], v[164:165], v[76:77] op_sel_hi:[0,1]
	v_pk_mul_f32 v[76:77], v[164:165], v[74:75] op_sel_hi:[0,1]
	v_mad_i64_i32 v[74:75], s[68:69], v177, s33, v[122:123]
	v_lshl_add_u64 v[74:75], v[74:75], 0, s[66:67]
	v_pk_mul_f32 v[94:95], v[164:165], v[94:95] op_sel_hi:[0,1]
	v_pk_mul_f32 v[96:97], v[164:165], v[96:97] op_sel_hi:[0,1]
	v_lshl_add_u64 v[74:75], v[74:75], 0, s[36:37]
	v_lshl_add_u64 v[80:81], v[74:75], 0, v[142:143]
	v_cvt_pk_bf16_f32 v74, v96, v97
	v_cvt_pk_bf16_f32 v75, v94, v95
	v_cvt_pk_bf16_f32 v76, v76, v77
	v_cvt_pk_bf16_f32 v77, v78, v79
	s_nop 0
; __device__ __forceinline__ unsigned pk2(float lo, float hi) { f32x2 v = {lo, hi}; bf16x2_t b = __builtin_convertvector(v, bf16x2_t); return __builtin_bit_cast(unsigned, b); }
; __device__ __forceinline__ void swap16(unsigned& a, unsigned& b) { auto r = __builtin_amdgcn_permlane16_swap(a, b, false, false); a = r[0]; b = r[1]; }
;     __device__ __forceinline__ void operator()(const f32x4 (&acc)[2][2][4][2], const Unit& u, int wr, int wc, int fr, int fq) const {
;     ...
;         if (u.pn < 8) {
; #pragma unroll
;             for (int ai = 0; ai < 2; ++ai)
; #pragma unroll
;                 for (int m = 0; m < 4; ++m) {
;                     const int row = row0 + ai * HALF + m * 16, pos = row & (SEQ - 1);
; #pragma unroll
;                     for (int bj = 0; bj < 2; ++bj) {
;                         const int g = 4 * bj + wc, hl = g >> 1, d0 = (g & 1) * 16 + 4 * fq;
;                         const f32x4 c = *(const f32x4*)(cosT + pos * 32 + d0), s = *(const f32x4*)(sinT + pos * 32 + d0);
;                         const f32x4 x1 = acc[ai][bj][m][0], x2 = acc[ai][bj][m][1];
;                         const float qs = (u.pn < 4) ? 0.125f * 1.4426950408889634f : 1.0f;
;                         const f32x4 o1 = (x1 * c - x2 * s) * qs, o2 = (x2 * c + x1 * s) * qs;
;                         bf16_t* p = P + (size_t)row * INC + u.pn * BM + hl * 64 + d0;
;                         unsigned a0 = pk2(o1[0], o1[1]), a1 = pk2(o1[2], o1[3]), b0 = pk2(o2[0], o2[1]), b1 = pk2(o2[2], o2[3]);
;                         swap16(a0, b0); swap16(a1, b1);
;                         *(u32x4*)(p + ((fq & 1) ? 28 : 0)) = (u32x4){a0, a1, b0, b1};
;                         asm volatile("" ::: "memory");
;                     }
;                 }
	v_permlane16_swap_b32_e32 v74, v76
	v_permlane16_swap_b32_e32 v75, v77
	v_lshl_add_u64 v[86:87], v[80:81], 0, v[144:145]
	global_store_dwordx4 v[86:87], v[74:77], off
	v_pk_mul_f32 v[82:83], v[68:69], v[232:233]
	v_pk_mul_f32 v[84:85], v[66:67], v[230:231]
	v_pk_fma_f32 v[82:83], v[72:73], v[228:229], v[82:83] neg_lo:[0,0,1] neg_hi:[0,0,1]
	v_pk_fma_f32 v[84:85], v[70:71], v[226:227], v[84:85] neg_lo:[0,0,1] neg_hi:[0,0,1]
	v_pk_mul_f32 v[72:73], v[72:73], v[232:233]
	v_pk_mul_f32 v[70:71], v[70:71], v[230:231]
	v_pk_fma_f32 v[68:69], v[68:69], v[228:229], v[72:73]
	v_pk_fma_f32 v[66:67], v[66:67], v[226:227], v[70:71]
	v_pk_mul_f32 v[82:83], v[164:165], v[82:83] op_sel_hi:[0,1]
	v_pk_mul_f32 v[84:85], v[164:165], v[84:85] op_sel_hi:[0,1]
	v_pk_mul_f32 v[70:71], v[164:165], v[68:69] op_sel_hi:[0,1]
	v_pk_mul_f32 v[68:69], v[164:165], v[66:67] op_sel_hi:[0,1]
	v_cvt_pk_bf16_f32 v66, v84, v85
	v_cvt_pk_bf16_f32 v67, v82, v83
	v_cvt_pk_bf16_f32 v68, v68, v69
	v_cvt_pk_bf16_f32 v69, v70, v71
	s_nop 0
	v_permlane16_swap_b32_e32 v66, v68
	v_permlane16_swap_b32_e32 v67, v69
	global_store_dwordx4 v[86:87], v[66:69], off offset:256
	s_nop 1
	v_lshl_add_u64 v[66:67], v[134:135], 0, v[0:1]
	v_lshl_add_u64 v[68:69], v[136:137], 0, v[0:1]
	v_lshlrev_b32_e32 v0, 7, v175
	v_and_b32_e32 v0, 0xfef80, v0
	v_pk_mul_f32 v[78:79], v[60:61], v[240:241]
	v_pk_mul_f32 v[80:81], v[58:59], v[238:239]
	v_pk_fma_f32 v[78:79], v[64:65], v[236:237], v[78:79] neg_lo:[0,0,1] neg_hi:[0,0,1]
	v_pk_fma_f32 v[80:81], v[62:63], v[234:235], v[80:81] neg_lo:[0,0,1] neg_hi:[0,0,1]
	v_pk_mul_f32 v[64:65], v[64:65], v[240:241]
	v_pk_mul_f32 v[62:63], v[62:63], v[238:239]
	v_pk_fma_f32 v[60:61], v[60:61], v[236:237], v[64:65]
	v_pk_fma_f32 v[58:59], v[58:59], v[234:235], v[62:63]
	v_pk_mul_f32 v[62:63], v[164:165], v[60:61] op_sel_hi:[0,1]
	v_pk_mul_f32 v[60:61], v[164:165], v[58:59] op_sel_hi:[0,1]
	v_mad_i64_i32 v[58:59], s[68:69], v176, s33, v[122:123]
	v_lshl_add_u64 v[58:59], v[58:59], 0, s[66:67]
	v_pk_mul_f32 v[78:79], v[164:165], v[78:79] op_sel_hi:[0,1]
	v_pk_mul_f32 v[80:81], v[164:165], v[80:81] op_sel_hi:[0,1]
	v_lshl_add_u64 v[58:59], v[58:59], 0, s[36:37]
	v_lshl_add_u64 v[64:65], v[58:59], 0, v[142:143]
	v_cvt_pk_bf16_f32 v58, v80, v81
	v_cvt_pk_bf16_f32 v59, v78, v79
	v_cvt_pk_bf16_f32 v60, v60, v61
	v_cvt_pk_bf16_f32 v61, v62, v63
	s_nop 0
	v_permlane16_swap_b32_e32 v58, v60
	v_permlane16_swap_b32_e32 v59, v61
	v_lshl_add_u64 v[70:71], v[64:65], 0, v[144:145]
	global_store_dwordx4 v[70:71], v[58:61], off
	v_pk_mul_f32 v[66:67], v[52:53], v[240:241]
	v_pk_mul_f32 v[68:69], v[50:51], v[238:239]
	v_pk_fma_f32 v[66:67], v[56:57], v[236:237], v[66:67] neg_lo:[0,0,1] neg_hi:[0,0,1]
	v_pk_fma_f32 v[68:69], v[54:55], v[234:235], v[68:69] neg_lo:[0,0,1] neg_hi:[0,0,1]
	v_pk_mul_f32 v[56:57], v[56:57], v[240:241]
	v_pk_mul_f32 v[54:55], v[54:55], v[238:239]
	v_pk_fma_f32 v[52:53], v[52:53], v[236:237], v[56:57]
	v_pk_fma_f32 v[50:51], v[50:51], v[234:235], v[54:55]
	v_pk_mul_f32 v[66:67], v[164:165], v[66:67] op_sel_hi:[0,1]
	v_pk_mul_f32 v[68:69], v[164:165], v[68:69] op_sel_hi:[0,1]
	v_pk_mul_f32 v[54:55], v[164:165], v[52:53] op_sel_hi:[0,1]
	v_pk_mul_f32 v[52:53], v[164:165], v[50:51] op_sel_hi:[0,1]
	v_cvt_pk_bf16_f32 v50, v68, v69
	v_cvt_pk_bf16_f32 v51, v66, v67
	v_cvt_pk_bf16_f32 v52, v52, v53
	v_cvt_pk_bf16_f32 v53, v54, v55
	s_nop 0
	v_permlane16_swap_b32_e32 v50, v52
	v_permlane16_swap_b32_e32 v51, v53
	global_store_dwordx4 v[70:71], v[50:53], off offset:256
	s_nop 1
	v_lshl_add_u64 v[50:51], v[134:135], 0, v[0:1]
	v_lshl_add_u64 v[52:53], v[136:137], 0, v[0:1]
	v_lshlrev_b32_e32 v0, 7, v174
	v_and_b32_e32 v0, 0xff780, v0
	v_pk_mul_f32 v[62:63], v[44:45], v[248:249]
	v_pk_mul_f32 v[64:65], v[42:43], v[246:247]
	v_pk_fma_f32 v[62:63], v[48:49], v[244:245], v[62:63] neg_lo:[0,0,1] neg_hi:[0,0,1]
	v_pk_fma_f32 v[64:65], v[46:47], v[242:243], v[64:65] neg_lo:[0,0,1] neg_hi:[0,0,1]
	v_pk_mul_f32 v[48:49], v[48:49], v[248:249]
	v_pk_mul_f32 v[46:47], v[46:47], v[246:247]
	v_pk_fma_f32 v[44:45], v[44:45], v[244:245], v[48:49]
	v_pk_fma_f32 v[42:43], v[42:43], v[242:243], v[46:47]
	v_pk_mul_f32 v[46:47], v[164:165], v[44:45] op_sel_hi:[0,1]
	v_pk_mul_f32 v[44:45], v[164:165], v[42:43] op_sel_hi:[0,1]
	v_mad_i64_i32 v[42:43], s[68:69], v175, s33, v[122:123]
	v_lshl_add_u64 v[42:43], v[42:43], 0, s[66:67]
	v_pk_mul_f32 v[62:63], v[164:165], v[62:63] op_sel_hi:[0,1]
	v_pk_mul_f32 v[64:65], v[164:165], v[64:65] op_sel_hi:[0,1]
	v_lshl_add_u64 v[42:43], v[42:43], 0, s[36:37]
	v_lshl_add_u64 v[48:49], v[42:43], 0, v[142:143]
	v_cvt_pk_bf16_f32 v42, v64, v65
	v_cvt_pk_bf16_f32 v43, v62, v63
	v_cvt_pk_bf16_f32 v44, v44, v45
	v_cvt_pk_bf16_f32 v45, v46, v47
	s_nop 0
	v_permlane16_swap_b32_e32 v42, v44
	v_permlane16_swap_b32_e32 v43, v45
	v_lshl_add_u64 v[54:55], v[48:49], 0, v[144:145]
	global_store_dwordx4 v[54:55], v[42:45], off
	v_pk_mul_f32 v[50:51], v[36:37], v[248:249]
	v_pk_mul_f32 v[52:53], v[34:35], v[246:247]
	v_pk_fma_f32 v[50:51], v[40:41], v[244:245], v[50:51] neg_lo:[0,0,1] neg_hi:[0,0,1]
	v_pk_fma_f32 v[52:53], v[38:39], v[242:243], v[52:53] neg_lo:[0,0,1] neg_hi:[0,0,1]
	v_pk_mul_f32 v[40:41], v[40:41], v[248:249]
	v_pk_mul_f32 v[38:39], v[38:39], v[246:247]
	v_pk_fma_f32 v[36:37], v[36:37], v[244:245], v[40:41]
	v_pk_fma_f32 v[34:35], v[34:35], v[242:243], v[38:39]
	v_pk_mul_f32 v[50:51], v[164:165], v[50:51] op_sel_hi:[0,1]
	v_pk_mul_f32 v[52:53], v[164:165], v[52:53] op_sel_hi:[0,1]
	v_pk_mul_f32 v[38:39], v[164:165], v[36:37] op_sel_hi:[0,1]
	v_pk_mul_f32 v[36:37], v[164:165], v[34:35] op_sel_hi:[0,1]
	v_cvt_pk_bf16_f32 v34, v52, v53
	v_cvt_pk_bf16_f32 v35, v50, v51
	v_cvt_pk_bf16_f32 v36, v36, v37
	v_cvt_pk_bf16_f32 v37, v38, v39
	s_nop 0
	v_permlane16_swap_b32_e32 v34, v36
	v_permlane16_swap_b32_e32 v35, v37
	global_store_dwordx4 v[54:55], v[34:37], off offset:256
	s_nop 1
	v_lshl_add_u64 v[34:35], v[134:135], 0, v[0:1]
	v_lshl_add_u64 v[36:37], v[136:137], 0, v[0:1]
	v_lshlrev_b32_e32 v0, 7, v173
	v_and_b32_e32 v0, 0xfff80, v0
	s_waitcnt vmcnt(10)
; __device__ __forceinline__ unsigned pk2(float lo, float hi) { f32x2 v = {lo, hi}; bf16x2_t b = __builtin_convertvector(v, bf16x2_t); return __builtin_bit_cast(unsigned, b); }
; __device__ __forceinline__ void swap16(unsigned& a, unsigned& b) { auto r = __builtin_amdgcn_permlane16_swap(a, b, false, false); a = r[0]; b = r[1]; }
; template <class Epi, class Sched>
; __device__ __forceinline__ void gemm_phase(LAS unsigned char* lds, const Gemm g, const Sched& S, const Epi& E) {
;     ...
;         if (!has_next) break;
; #pragma unroll
;         for (int a = 0; a < 2; ++a)
; #pragma unroll
;             for (int b = 0; b < 2; ++b)
; #pragma unroll
;                 for (int m = 0; m < 4; ++m)
; #pragma unroll
;                     for (int n = 0; n < 2; ++n) acc[a][b][m][n] = (f32x4){0.f, 0.f, 0.f, 0.f};
;         cur = nxt; cA = nA; cB = nB; ++ui;
;     __device__ __forceinline__ void operator()(const f32x4 (&acc)[2][2][4][2], const Unit& u, int wr, int wc, int fr, int fq) const {
;     ...
;         if (u.pn < 8) {
; #pragma unroll
;             for (int ai = 0; ai < 2; ++ai)
; #pragma unroll
;                 for (int m = 0; m < 4; ++m) {
;                     const int row = row0 + ai * HALF + m * 16, pos = row & (SEQ - 1);
; #pragma unroll
;                     for (int bj = 0; bj < 2; ++bj) {
;                         const int g = 4 * bj + wc, hl = g >> 1, d0 = (g & 1) * 16 + 4 * fq;
;                         const f32x4 c = *(const f32x4*)(cosT + pos * 32 + d0), s = *(const f32x4*)(sinT + pos * 32 + d0);
;                         const f32x4 x1 = acc[ai][bj][m][0], x2 = acc[ai][bj][m][1];
;                         const float qs = (u.pn < 4) ? 0.125f * 1.4426950408889634f : 1.0f;
;                         const f32x4 o1 = (x1 * c - x2 * s) * qs, o2 = (x2 * c + x1 * s) * qs;
;                         bf16_t* p = P + (size_t)row * INC + u.pn * BM + hl * 64 + d0;
;                         unsigned a0 = pk2(o1[0], o1[1]), a1 = pk2(o1[2], o1[3]), b0 = pk2(o2[0], o2[1]), b1 = pk2(o2[2], o2[3]);
;                         swap16(a0, b0); swap16(a1, b1);
;                         *(u32x4*)(p + ((fq & 1) ? 28 : 0)) = (u32x4){a0, a1, b0, b1};
;                         asm volatile("" ::: "memory");
;                     }
;                 }
	v_pk_mul_f32 v[46:47], v[28:29], v[198:199]
	v_pk_mul_f32 v[48:49], v[26:27], v[196:197]
	v_pk_fma_f32 v[46:47], v[32:33], v[194:195], v[46:47] neg_lo:[0,0,1] neg_hi:[0,0,1]
	v_pk_fma_f32 v[48:49], v[30:31], v[192:193], v[48:49] neg_lo:[0,0,1] neg_hi:[0,0,1]
	v_pk_mul_f32 v[32:33], v[32:33], v[198:199]
	v_pk_mul_f32 v[30:31], v[30:31], v[196:197]
	v_pk_fma_f32 v[28:29], v[28:29], v[194:195], v[32:33]
	v_pk_fma_f32 v[26:27], v[26:27], v[192:193], v[30:31]
	v_pk_mul_f32 v[30:31], v[164:165], v[28:29] op_sel_hi:[0,1]
	v_pk_mul_f32 v[28:29], v[164:165], v[26:27] op_sel_hi:[0,1]
	v_mad_i64_i32 v[26:27], s[68:69], v174, s33, v[122:123]
	v_lshl_add_u64 v[26:27], v[26:27], 0, s[66:67]
	v_pk_mul_f32 v[46:47], v[164:165], v[46:47] op_sel_hi:[0,1]
	v_pk_mul_f32 v[48:49], v[164:165], v[48:49] op_sel_hi:[0,1]
	v_lshl_add_u64 v[26:27], v[26:27], 0, s[36:37]
	v_lshl_add_u64 v[32:33], v[26:27], 0, v[142:143]
	v_cvt_pk_bf16_f32 v26, v48, v49
	v_cvt_pk_bf16_f32 v27, v46, v47
	v_cvt_pk_bf16_f32 v28, v28, v29
	v_cvt_pk_bf16_f32 v29, v30, v31
	s_nop 0
	v_permlane16_swap_b32_e32 v26, v28
	v_permlane16_swap_b32_e32 v27, v29
	v_lshl_add_u64 v[38:39], v[32:33], 0, v[144:145]
	global_store_dwordx4 v[38:39], v[26:29], off
	v_pk_mul_f32 v[34:35], v[20:21], v[198:199]
	v_pk_mul_f32 v[36:37], v[18:19], v[196:197]
	v_pk_fma_f32 v[34:35], v[24:25], v[194:195], v[34:35] neg_lo:[0,0,1] neg_hi:[0,0,1]
	v_pk_fma_f32 v[36:37], v[22:23], v[192:193], v[36:37] neg_lo:[0,0,1] neg_hi:[0,0,1]
	v_pk_mul_f32 v[24:25], v[24:25], v[198:199]
	v_pk_mul_f32 v[22:23], v[22:23], v[196:197]
	v_pk_fma_f32 v[20:21], v[20:21], v[194:195], v[24:25]
	v_pk_fma_f32 v[18:19], v[18:19], v[192:193], v[22:23]
	v_pk_mul_f32 v[34:35], v[164:165], v[34:35] op_sel_hi:[0,1]
	v_pk_mul_f32 v[36:37], v[164:165], v[36:37] op_sel_hi:[0,1]
	v_pk_mul_f32 v[22:23], v[164:165], v[20:21] op_sel_hi:[0,1]
	v_pk_mul_f32 v[20:21], v[164:165], v[18:19] op_sel_hi:[0,1]
	v_cvt_pk_bf16_f32 v18, v36, v37
	v_cvt_pk_bf16_f32 v19, v34, v35
	v_cvt_pk_bf16_f32 v20, v20, v21
	v_cvt_pk_bf16_f32 v21, v22, v23
	s_nop 0
	v_permlane16_swap_b32_e32 v18, v20
	v_permlane16_swap_b32_e32 v19, v21
	global_store_dwordx4 v[38:39], v[18:21], off offset:256
	s_nop 1
	v_lshl_add_u64 v[18:19], v[134:135], 0, v[0:1]
	v_lshl_add_u64 v[20:21], v[136:137], 0, v[0:1]
	s_waitcnt vmcnt(10)
	v_pk_mul_f32 v[30:31], v[12:13], v[206:207]
	v_pk_mul_f32 v[32:33], v[10:11], v[204:205]
	v_pk_fma_f32 v[30:31], v[16:17], v[202:203], v[30:31] neg_lo:[0,0,1] neg_hi:[0,0,1]
	v_pk_fma_f32 v[32:33], v[14:15], v[200:201], v[32:33] neg_lo:[0,0,1] neg_hi:[0,0,1]
	v_pk_mul_f32 v[16:17], v[16:17], v[206:207]
	v_pk_mul_f32 v[14:15], v[14:15], v[204:205]
	v_pk_fma_f32 v[12:13], v[12:13], v[202:203], v[16:17]
	v_pk_fma_f32 v[10:11], v[10:11], v[200:201], v[14:15]
	v_pk_mul_f32 v[14:15], v[164:165], v[12:13] op_sel_hi:[0,1]
	v_pk_mul_f32 v[12:13], v[164:165], v[10:11] op_sel_hi:[0,1]
	v_mad_i64_i32 v[10:11], s[68:69], v173, s33, v[122:123]
	v_lshl_add_u64 v[10:11], v[10:11], 0, s[66:67]
	v_pk_mul_f32 v[30:31], v[164:165], v[30:31] op_sel_hi:[0,1]
	v_pk_mul_f32 v[32:33], v[164:165], v[32:33] op_sel_hi:[0,1]
	v_lshl_add_u64 v[10:11], v[10:11], 0, s[36:37]
	v_lshl_add_u64 v[16:17], v[10:11], 0, v[142:143]
	v_cvt_pk_bf16_f32 v10, v32, v33
	v_cvt_pk_bf16_f32 v11, v30, v31
	v_cvt_pk_bf16_f32 v12, v12, v13
	v_cvt_pk_bf16_f32 v13, v14, v15
	s_nop 0
	v_permlane16_swap_b32_e32 v10, v12
	v_permlane16_swap_b32_e32 v11, v13
	v_lshl_add_u64 v[22:23], v[16:17], 0, v[144:145]
	global_store_dwordx4 v[22:23], v[10:13], off
	v_pk_mul_f32 v[18:19], v[4:5], v[206:207]
	v_pk_mul_f32 v[20:21], v[2:3], v[204:205]
	v_pk_fma_f32 v[18:19], v[8:9], v[202:203], v[18:19] neg_lo:[0,0,1] neg_hi:[0,0,1]
	v_pk_fma_f32 v[20:21], v[6:7], v[200:201], v[20:21] neg_lo:[0,0,1] neg_hi:[0,0,1]
	v_pk_mul_f32 v[8:9], v[8:9], v[206:207]
	v_pk_mul_f32 v[6:7], v[6:7], v[204:205]
	v_pk_fma_f32 v[4:5], v[4:5], v[202:203], v[8:9]
	v_pk_fma_f32 v[2:3], v[2:3], v[200:201], v[6:7]
	v_pk_mul_f32 v[18:19], v[164:165], v[18:19] op_sel_hi:[0,1]
	v_pk_mul_f32 v[20:21], v[164:165], v[20:21] op_sel_hi:[0,1]
	v_pk_mul_f32 v[6:7], v[164:165], v[4:5] op_sel_hi:[0,1]
	v_pk_mul_f32 v[4:5], v[164:165], v[2:3] op_sel_hi:[0,1]
	v_cvt_pk_bf16_f32 v2, v20, v21
	v_cvt_pk_bf16_f32 v3, v18, v19
	v_cvt_pk_bf16_f32 v4, v4, v5
	v_cvt_pk_bf16_f32 v5, v6, v7
	s_nop 0
	v_permlane16_swap_b32_e32 v2, v4
	v_permlane16_swap_b32_e32 v3, v5
	global_store_dwordx4 v[22:23], v[2:5], off offset:256
	s_andn2_b64 vcc, exec, s[42:43]
	s_mov_b64 s[42:43], -1
	s_cbranch_vccnz .LBB0_152
